# GQA attention: the 4 LDS-spilled q fragments now live in otherwise unused VGPRs v220-235, no per-tile LDS re-read; counted lgkmcnt waits
# speedup vs baseline: 1.0090x; 1.0090x over previous
; __device__ __forceinline__ int v_st(int k, int c) { const int kk = (k & ~0xC) | ((k & 4) << 1) | ((k & 8) >> 1); return ((kk >> 3) * 4 + (c >> 5)) * 512 + ((kk & 7) * 32 + (c & 31)) * 2; }
; __device__ __forceinline__ int v_rd_base(int lane) { return ((lane & 3) << 3) | (((lane >> 2) & 3) << 6) | (((lane >> 4) & 1) << 5) | (((lane >> 5) & 1) << 8); }
; #define SWRITE(b, i) do { *(bf16x8*)(V_lds + (b) * SHM_V + vst0) = sr_[i].vs0; *(bf16x8*)(V_lds + (b) * SHM_V + vst1) = sr_[i].vs1; \
;     *(bf16x8*)(K_lds + (b) * SHM_K + kdst0) = sr_[i].ks0; *(bf16x8*)(K_lds + (b) * SHM_K + kdst0 + 32 * KW * 2) = sr_[i].ks1; \
;     if constexpr (KW == 192) *(bf16x8*)(K_lds + (b) * SHM_K + kdst2) = sr_[i].ks2; } while (0)
; #define VM0() asm volatile("s_waitcnt vmcnt(0)" ::: "memory")
; #define WGBAR() asm volatile("s_waitcnt lgkmcnt(0)\n\ts_barrier" ::: "memory")
; template <int DQK, int KW, bool DIFF, int SDEPTH, int QSP, int NBUF>
; __device__ __forceinline__ void attn_unit(const UnitP& P, char* lds) {
;     ...
;   { const bf16_t* Qp = P.Qw + (long)r32 * P.ldq + hi * 8;
; #pragma unroll
;     for (int d0 = 0; d0 < NQR; ++d0) qr[d0] = *reinterpret_cast<const bf16x8*>(Qp + d0 * 16);
; #pragma unroll
;     for (int d0 = NQR; d0 < DQK / 16; ++d0) *reinterpret_cast<bf16x8*>(qsp + (d0 - NQR) * 1024) = *reinterpret_cast<const bf16x8*>(Qp + d0 * 16); }
;   const int sr = tid >> 4, sc = (tid & 15) * 8, vst0 = v_st(sr, sc), vst1 = v_st(32 + sr, sc);
;   const int vb0 = (int)(uintptr_t)V_lds + v_rd_base(lane);
;   int kb[4];
; #pragma unroll
;   for (int q = 0; q < 4; ++q) kb[q] = coffB + kswz<KW>(r32, q * 32 + hi * 16);
;   const unsigned voff = (unsigned)(sr * P.ldv + sc) * 2u, koff = (unsigned)(sr * P.ldk0 + sc) * 2u, koff2 = (unsigned)((tid >> 3) * P.ldk1 + (tid & 7) * 8) * 2u;
;   const int kdst0 = kswz<KW>(sr, sc * 2), kdst2 = kswz<KW>(tid >> 3, 256 + (tid & 7) * 16);
;     ...
;     SLOAD(0, 0); VM0(); SWRITE(0, 0); SLOAD(0, 1); WGBAR();
.LBB0_285:
	s_ashr_i32 s28, s27, 4
	s_and_b32 s29, s27, 15
	s_add_u32 s8, s8, s20
	s_mul_i32 s30, s28, 0x900
	s_addc_u32 s9, s9, s21
	s_mul_hi_i32 s2, s28, 0x900
	s_add_u32 s8, s8, s30
	s_addc_u32 s9, s9, s2
	s_add_u32 s30, s30, s6
	s_addc_u32 s31, s2, s7
	s_lshl_b64 s[42:43], s[8:9], 11
	s_lshl_b64 s[8:9], s[8:9], 12
	s_add_u32 s7, s10, s8
	s_addc_u32 s8, s11, s9
	s_lshl_b32 s2, s29, 7
	s_lshl_b32 s9, s29, 8
	s_add_u32 s36, s7, s9
	s_addc_u32 s37, s8, 0
	s_lshl_b64 s[30:31], s[30:31], 10
	s_add_u32 s8, s12, s30
	s_addc_u32 s9, s13, s31
	s_lshl_b32 s7, s27, 6
	s_and_b32 s7, s7, 0x300
	v_mov_b32_e32 v96, v184
	s_add_u32 s8, s8, s7
	s_addc_u32 s9, s9, 0
	v_and_b32_e32 v150, 31, v96
	v_bfe_u32 v151, v96, 5, 1
	v_lshlrev_b32_e32 v0, 12, v150
	s_add_u32 s27, s14, s30
	s_waitcnt vmcnt(0)
	v_lshl_add_u64 v[2:3], s[36:37], 0, v[0:1]
	v_lshlrev_b32_e32 v146, 4, v151
	v_mov_b32_e32 v147, v1
	v_lshlrev_b32_e32 v37, 3, v96
	s_addc_u32 s29, s15, s31
	v_lshl_add_u64 v[34:35], v[2:3], 0, v[146:147]
	v_and_b32_e32 v0, 0x78, v37
	s_add_u32 s30, s27, s7
	global_load_dwordx4 v[2:5], v[34:35], off offset:128
	global_load_dwordx4 v[6:9], v[34:35], off offset:160
	global_load_dwordx4 v[10:13], v[34:35], off offset:192
	global_load_dwordx4 v[14:17], v[34:35], off offset:224
	v_ashrrev_i32_e32 v36, 4, v96
	v_lshlrev_b32_e32 v0, 1, v0
	s_addc_u32 s31, s29, 0
	v_lshl_or_b32 v66, v36, 10, v0
	v_mov_b32_e32 v67, v1
	v_lshl_add_u64 v[70:71], s[30:31], 0, v[66:67]
	s_mov_b32 s27, 0x8000
	v_add_co_u32_e32 v18, vcc, s27, v70
	v_lshl_add_u64 v[68:69], s[8:9], 0, v[66:67]
	s_nop 0
	v_addc_co_u32_e32 v19, vcc, 0, v71, vcc
	v_add_co_u32_e32 v30, vcc, s27, v68
	global_load_dwordx4 v[18:21], v[18:19], off
	s_nop 0
	global_load_dwordx4 v[22:25], v66, s[30:31]
	global_load_dwordx4 v[26:29], v66, s[8:9]
	v_addc_co_u32_e32 v31, vcc, 0, v69, vcc
	global_load_dwordx4 v[30:33], v[30:31], off
	v_lshlrev_b32_e32 v38, 6, v96
	global_load_dwordx4 v[102:105], v[34:35], off
	global_load_dwordx4 v[110:113], v[34:35], off offset:32
	global_load_dwordx4 v[106:109], v[34:35], off offset:64
	global_load_dwordx4 v[98:101], v[34:35], off offset:96
	v_and_b32_e32 v152, 0xfffff000, v38
	v_and_b32_e32 v38, 0xfffff0, v36
	v_lshlrev_b32_e32 v39, 1, v36
	v_lshrrev_b32_e32 v40, 1, v36
	v_and_b32_e32 v41, 3, v36
	v_add_u32_e32 v42, 32, v36
	v_and_b32_e32 v147, 63, v96
	v_and_or_b32 v38, v39, 8, v38
	v_and_or_b32 v39, v40, 4, v41
	v_and_b32_e32 v40, 0xfffff0, v42
	v_lshlrev_b32_e32 v41, 1, v42
	s_add_i32 s8, 0, 0x18800
	v_lshlrev_b32_e32 v97, 4, v147
	v_and_or_b32 v40, v41, 8, v40
	v_add_u32_e32 v34, s8, v152
	v_bfe_u32 v37, v37, 5, 2
	v_lshrrev_b32_e32 v38, 1, v38
	v_lshrrev_b32_e32 v40, 1, v40
	v_add_u32_e32 v157, v34, v97
	v_or_b32_e32 v38, v38, v37
	v_or_b32_e32 v37, v40, v37
	v_lshlrev_b32_e32 v39, 6, v39
	v_lshlrev_b32_e32 v38, 9, v38
	s_mov_b32 s8, 0x10000
	v_lshlrev_b32_e32 v84, 8, v150
	s_mov_b32 s33, 0x42b504f3
	s_mov_b32 s48, 0
	s_mov_b32 s49, s48
	s_mov_b32 s50, s48
	s_mov_b32 s51, s48
	s_waitcnt vmcnt(11)
	ds_write_b128 v157, v[2:5]
	s_waitcnt vmcnt(10)
	ds_write_b128 v157, v[6:9] offset:1024
	s_waitcnt vmcnt(9)
	ds_write_b128 v157, v[10:13] offset:2048
	s_waitcnt vmcnt(8)
	ds_write_b128 v157, v[14:17] offset:3072
	v_mov_b64_e32 v[220:221], v[2:3]
	v_mov_b64_e32 v[222:223], v[4:5]
	v_mov_b64_e32 v[224:225], v[6:7]
	v_mov_b64_e32 v[226:227], v[8:9]
	v_mov_b64_e32 v[228:229], v[10:11]
	v_mov_b64_e32 v[230:231], v[12:13]
	v_mov_b64_e32 v[232:233], v[14:15]
	v_mov_b64_e32 v[234:235], v[16:17]
	v_lshlrev_b32_e32 v3, 4, v96
	v_lshlrev_b32_e32 v2, 9, v37
	v_and_b32_e32 v85, 0x70, v3
	v_and_b32_e32 v3, 48, v0
	v_or3_b32 v159, v38, v39, v3
	v_or3_b32 v160, v2, v39, v3
	v_lshlrev_b32_e32 v2, 8, v36
	v_and_b32_e32 v3, 0x70, v96
	v_bitop3_b32 v161, v0, v2, v3 bitop3:0xde
	v_add_co_u32_e32 v2, vcc, s8, v70
	v_add_u32_e32 v148, 0, v159
	s_nop 0
	v_addc_co_u32_e32 v3, vcc, 0, v71, vcc
	v_add_u32_e32 v149, 0, v160
	v_add_u32_e32 v162, 0, v161
	v_add_co_u32_e32 v4, vcc, s84, v70
	s_waitcnt vmcnt(0)
	s_waitcnt vmcnt(6)
	ds_write_b128 v148, v[22:25]
	ds_write_b128 v149, v[18:21]
	s_waitcnt vmcnt(5)
	ds_write_b128 v162, v[26:29] offset:49152
	s_waitcnt vmcnt(4)
	ds_write_b128 v162, v[30:33] offset:57344
	v_addc_co_u32_e32 v5, vcc, 0, v71, vcc
	global_load_dwordx4 v[50:53], v[2:3], off
	global_load_dwordx4 v[54:57], v[4:5], off
	v_add_co_u32_e32 v2, vcc, s8, v68
	v_bitop3_b32 v158, v146, v84, v85 bitop3:0xde
	s_nop 0
	v_addc_co_u32_e32 v3, vcc, 0, v69, vcc
	v_add_co_u32_e32 v4, vcc, s84, v68
	v_add_u32_e32 v18, 0, v158
	s_nop 0
	v_addc_co_u32_e32 v5, vcc, 0, v69, vcc
	global_load_dwordx4 v[58:61], v[2:3], off
	global_load_dwordx4 v[62:65], v[4:5], off
	s_waitcnt lgkmcnt(0)
	s_barrier
; #define SWRITE(b, i) do { *(bf16x8*)(V_lds + (b) * SHM_V + vst0) = sr_[i].vs0; *(bf16x8*)(V_lds + (b) * SHM_V + vst1) = sr_[i].vs1; \
;     *(bf16x8*)(K_lds + (b) * SHM_K + kdst0) = sr_[i].ks0; *(bf16x8*)(K_lds + (b) * SHM_K + kdst0 + 32 * KW * 2) = sr_[i].ks1; \
;     if constexpr (KW == 192) *(bf16x8*)(K_lds + (b) * SHM_K + kdst2) = sr_[i].ks2; } while (0)
; #define PSM(X0, X1, MN, AL, FIRST) do { if constexpr (DIFF) partialSM_ps<FIRST>(X0, X1, m_reg, AL, negm); else partialSM<DQK>(X0, X1, m_reg, MN, AL); } while (0)
; #define VM0() asm volatile("s_waitcnt vmcnt(0)" ::: "memory")
; #define WGBAR() asm volatile("s_waitcnt lgkmcnt(0)\n\ts_barrier" ::: "memory")
; template <int DQK> __device__ __forceinline__ void partialSM(f32x16& p0, f32x16& p1, float& m_reg, float& mn, float& alpha) {
;   constexpr float SCALE = Sc<DQK>::SCALE; constexpr float C = SCALE * 1.4426950408889634f;
;   float pmax = p0[0];
; #pragma unroll
;   for (int r = 1; r < 16; ++r) pmax = fmaxf(pmax, p0[r]);
; #pragma unroll
;   for (int r = 0; r < 16; ++r) pmax = fmaxf(pmax, p1[r]);
;   { auto rr = __builtin_amdgcn_permlane32_swap(__float_as_uint(pmax), __float_as_uint(pmax), false, false);
;     pmax = fmaxf(__uint_as_float(rr[0]), __uint_as_float(rr[1])); }
;   if (__builtin_expect(__all(pmax - m_reg <= THR / SCALE), 1)) { mn = m_reg; alpha = 1.f; }
;   else { mn = fmaxf(m_reg, pmax); alpha = __builtin_amdgcn_exp2f((m_reg - mn) * C); m_reg = mn; }
;   float mnC = -mn * C;
; #pragma unroll
;   for (int r = 0; r < 16; ++r) p0[r] = fmaf(p0[r], C, mnC);
; #pragma unroll
;   for (int r = 0; r < 16; ++r) p1[r] = fmaf(p1[r], C, mnC);
; #pragma unroll
;   for (int r = 0; r < 16; ++r) p0[r] = __builtin_amdgcn_exp2f(p0[r]);
; template <int DQK, int KW, bool DIFF, int SDEPTH, int QSP, int NBUF>
; __device__ __forceinline__ void attn_unit(const UnitP& P, char* lds) {
;     ...
;     qkt<DQK, KW, QSP>(pA0, pA1, K_lds, kb, qr, qsp, negm); PSM(pA0, pA1, mnA, alA, true);
;     VM0(); SWRITE(1, 0); if (2 < NT) SLOAD(0, 2); WGBAR();
	ds_read_b128 v[2:5], v18 offset:49152
	v_or_b32_e32 v6, 32, v146
	v_bitop3_b32 v163, v6, v84, v85 bitop3:0xde
	v_add_u32_e32 v86, 0, v163
	ds_read_b128 v[6:9], v86 offset:49152
	ds_read_b128 v[10:13], v86 offset:57344
	ds_read_b128 v[14:17], v18 offset:57344
	s_waitcnt vmcnt(7) lgkmcnt(3)
	v_mfma_f32_32x32x16_bf16 v[34:49], v[2:5], v[102:105], 0
	ds_read_b128 v[72:75], v18 offset:49280
	ds_read_b128 v[2:5], v18 offset:57472
	s_add_i32 s8, 0, 0x18000
	s_cmp_lg_u32 0, -1
	s_mov_b32 s52, s48
	s_mov_b32 s53, s48
	s_mov_b32 s54, s48
	s_waitcnt lgkmcnt(2)
	v_mfma_f32_32x32x16_bf16 v[18:33], v[14:17], v[102:105], 0
	v_or_b32_e32 v14, 64, v146
	v_bitop3_b32 v164, v14, v84, v85 bitop3:0xde
	v_add_u32_e32 v92, 0, v164
	ds_read_b128 v[14:17], v92 offset:49152
	ds_read_b128 v[76:79], v92 offset:57344
	ds_read_b128 v[80:83], v86 offset:49280
	s_mov_b32 s55, s48
	s_mov_b32 s56, s48
	s_waitcnt vmcnt(6)
	v_mfma_f32_32x32x16_bf16 v[34:49], v[6:9], v[110:113], v[34:49]
	ds_read_b128 v[6:9], v86 offset:57472
	s_mov_b32 s57, s48
	s_mov_b32 s58, s48
	s_mov_b32 s59, s48
	s_mov_b32 s60, s48
	s_mov_b32 s61, s48
	s_mov_b32 s62, s48
	v_mfma_f32_32x32x16_bf16 v[18:33], v[10:13], v[110:113], v[18:33]
	v_or_b32_e32 v10, 0x60, v146
	v_bitop3_b32 v165, v10, v84, v85 bitop3:0xde
	v_add_u32_e32 v93, 0, v165
	ds_read_b128 v[10:13], v93 offset:49152
	ds_read_b128 v[84:87], v93 offset:57344
	ds_read_b128 v[88:91], v92 offset:49280
	s_mov_b32 s63, s48
	s_mov_b32 s27, 2
	s_waitcnt vmcnt(5) lgkmcnt(6)
	v_mfma_f32_32x32x16_bf16 v[34:49], v[14:17], v[106:109], v[34:49]
	ds_read_b128 v[14:17], v92 offset:57472
	s_mov_b32 s30, 1
	v_cmp_gt_u32_e64 s[38:39], 32, v147
	v_mov_b32_e32 v156, 0
	s_waitcnt lgkmcnt(6)
	v_mfma_f32_32x32x16_bf16 v[18:33], v[76:79], v[106:109], v[18:33]
	ds_read_b128 v[76:79], v93 offset:49280
	ds_read_b128 v[92:95], v93 offset:57472
	s_waitcnt vmcnt(4) lgkmcnt(5)
	v_mfma_f32_32x32x16_bf16 v[34:49], v[10:13], v[98:101], v[34:49]
	s_waitcnt lgkmcnt(4)
	v_mfma_f32_32x32x16_bf16 v[18:33], v[84:87], v[98:101], v[18:33]
	ds_read_b128 v[10:13], v157
	ds_read_b128 v[84:87], v157 offset:1024
	s_waitcnt lgkmcnt(1)
	v_mfma_f32_32x32x16_bf16 v[34:49], v[72:75], v[10:13], v[34:49]
	v_mfma_f32_32x32x16_bf16 v[18:33], v[2:5], v[10:13], v[18:33]
	v_and_b32_e32 v2, 0x3fffffc0, v96
	v_lshl_add_u32 v153, v2, 2, s8
	v_lshlrev_b32_e32 v10, 3, v147
	v_and_b32_e32 v2, 0xc0, v97
	s_cselect_b32 s8, 0, 0
	v_lshl_add_u32 v155, v150, 2, v153
	s_waitcnt lgkmcnt(0)
	v_mfma_f32_32x32x16_bf16 v[34:49], v[80:83], v[84:87], v[34:49]
	v_mfma_f32_32x32x16_bf16 v[18:33], v[6:9], v[84:87], v[18:33]
	v_and_or_b32 v6, v10, 24, v2
	ds_read_b128 v[2:5], v157 offset:2048
	ds_read_b128 v[72:75], v157 offset:3072
	v_lshlrev_b32_e32 v7, 1, v96
	v_and_b32_e32 v7, 32, v7
	v_and_b32_e32 v8, 0x100, v10
	v_or3_b32 v6, v6, v7, v8
	s_waitcnt lgkmcnt(1)
	v_mfma_f32_32x32x16_bf16 v[34:49], v[88:91], v[2:5], v[34:49]
	v_add_u32_e32 v154, s8, v6
	s_mov_b32 s8, 0x28000
	s_waitcnt vmcnt(0)
	v_mfma_f32_32x32x16_bf16 v[18:33], v[14:17], v[2:5], v[18:33]
	v_mov_b64_e32 v[2:3], s[48:49]
	v_mov_b64_e32 v[16:17], s[62:63]
	v_mov_b64_e32 v[4:5], s[50:51]
	v_mov_b64_e32 v[6:7], s[52:53]
	v_mov_b64_e32 v[8:9], s[54:55]
	v_mov_b64_e32 v[10:11], s[56:57]
	v_mov_b64_e32 v[12:13], s[58:59]
	s_waitcnt lgkmcnt(0)
	v_mfma_f32_32x32x16_bf16 v[34:49], v[76:79], v[72:75], v[34:49]
	v_mov_b64_e32 v[14:15], s[60:61]
	v_readlane_b32 s56, v255, 9
	s_mov_b32 s51, 0x80000
	s_mov_b32 s52, 0xa0000
	s_movk_i32 s53, 0x4000
	s_mov_b32 s54, 0xf800000
	s_mov_b32 s49, s97
	v_mfma_f32_32x32x16_bf16 v[18:33], v[92:95], v[72:75], v[18:33]
	s_nop 3
	v_max_f32_e32 v72, v35, v35
	v_max_f32_e32 v73, v34, v34
	v_max_f32_e32 v72, v73, v72
	v_max3_f32 v72, v72, v36, v37
	v_max3_f32 v72, v72, v38, v39
	v_max3_f32 v72, v72, v40, v41
	v_max3_f32 v72, v72, v42, v43
	v_max3_f32 v72, v72, v44, v45
	v_max3_f32 v72, v72, v46, v47
	v_max3_f32 v72, v72, v48, v49
	v_max3_f32 v72, v72, v18, v19
	v_max3_f32 v72, v72, v20, v21
	v_max3_f32 v72, v72, v22, v23
	v_max3_f32 v72, v72, v24, v25
	v_max3_f32 v72, v72, v26, v27
	v_max3_f32 v72, v72, v28, v29
	v_max3_f32 v72, v72, v30, v31
	v_max3_f32 v74, v72, v32, v33
	v_add_co_u32_e32 v72, vcc, s87, v70
	v_readlane_b32 s57, v255, 10
	s_nop 0
	v_addc_co_u32_e32 v73, vcc, 0, v71, vcc
	v_add_co_u32_e32 v70, vcc, s8, v70
	s_nop 1
	v_addc_co_u32_e32 v71, vcc, 0, v71, vcc
	global_load_dwordx4 v[114:117], v[72:73], off
	global_load_dwordx4 v[118:121], v[70:71], off
	v_add_co_u32_e32 v70, vcc, s87, v68
	s_nop 1
	v_addc_co_u32_e32 v71, vcc, 0, v69, vcc
	v_add_co_u32_e32 v68, vcc, s8, v68
	s_mul_hi_i32 s8, s28, 0x240000
	s_nop 0
	v_addc_co_u32_e32 v69, vcc, 0, v69, vcc
	global_load_dwordx4 v[122:125], v[70:71], off
	global_load_dwordx4 v[126:129], v[68:69], off
	v_mov_b32_e32 v68, v74
	s_nop 1
	v_permlane32_swap_b32_e32 v74, v68
	v_max_f32_e32 v68, v68, v68
	v_max_f32_e32 v69, v74, v74
	v_max_f32_e32 v68, v69, v68
	v_add_f32_e32 v69, 0x7149f2ca, v68
	v_max_f32_e32 v68, 0xf149f2ca, v68
	v_cmp_ge_f32_e32 vcc, s33, v69
	v_sub_f32_e32 v69, 0xf149f2ca, v68
	v_mul_f32_e32 v69, 0x3e0293ee, v69
	v_exp_f32_e32 v69, v69
	s_cmp_eq_u64 vcc, exec
	s_cselect_b64 vcc, -1, 0
	v_cndmask_b32_e32 v167, v68, v185, vcc
	v_mul_f32_e32 v68, 0xbe0293ee, v167
	v_cndmask_b32_e64 v166, v69, 1.0, vcc
	v_mov_b32_e32 v69, v68
	v_fmac_f32_e32 v69, 0x3e0293ee, v49
	s_mul_i32 s28, s28, 0x240000
	s_lshl_b32 s6, s6, 10
	v_fmamk_f32 v34, v34, 0x3e0293ee, v68
	v_fmamk_f32 v35, v35, 0x3e0293ee, v68
	v_fmamk_f32 v36, v36, 0x3e0293ee, v68
	v_fmamk_f32 v37, v37, 0x3e0293ee, v68
	v_fmamk_f32 v38, v38, 0x3e0293ee, v68
	v_fmamk_f32 v39, v39, 0x3e0293ee, v68
	v_fmamk_f32 v40, v40, 0x3e0293ee, v68
	v_fmamk_f32 v41, v41, 0x3e0293ee, v68
	v_fmamk_f32 v42, v42, 0x3e0293ee, v68
	v_fmamk_f32 v43, v43, 0x3e0293ee, v68
	v_fmamk_f32 v44, v44, 0x3e0293ee, v68
	v_fmamk_f32 v45, v45, 0x3e0293ee, v68
	v_fmamk_f32 v46, v46, 0x3e0293ee, v68
	v_fmamk_f32 v47, v47, 0x3e0293ee, v68
	v_fmamk_f32 v48, v48, 0x3e0293ee, v68
	v_pk_fma_f32 v[144:145], v[18:19], s[90:91], v[68:69] op_sel_hi:[1,0,0]
	v_add_u32_e32 v18, 0x10000, v162
	s_add_u32 s6, s28, s6
	v_exp_f32_e32 v193, v34
	v_exp_f32_e32 v195, v35
	v_exp_f32_e32 v183, v36
	v_exp_f32_e32 v194, v37
	v_exp_f32_e32 v181, v38
	v_exp_f32_e32 v192, v39
	v_exp_f32_e32 v180, v40
	v_exp_f32_e32 v182, v41
	v_exp_f32_e32 v177, v42
	v_exp_f32_e32 v179, v43
	v_exp_f32_e32 v175, v44
	v_exp_f32_e32 v178, v45
	v_exp_f32_e32 v173, v46
	v_exp_f32_e32 v176, v47
	v_exp_f32_e32 v172, v48
	v_exp_f32_e32 v174, v69
	s_waitcnt vmcnt(7)
	ds_write_b128 v148, v[50:53] offset:16384
	s_waitcnt vmcnt(6)
	ds_write_b128 v149, v[54:57] offset:16384
	s_waitcnt vmcnt(5)
	ds_write_b128 v18, v[58:61]
	s_waitcnt vmcnt(4)
	ds_write_b128 v18, v[62:65] offset:8192
	s_addc_u32 s8, s8, 0
	s_or_b32 s6, s6, s7
	s_waitcnt lgkmcnt(0)
	s_barrier
; __device__ __forceinline__ void finishSM(f32x16& p0, f32x16& p1, float alpha, float& l_reg, bf16x8& pa0, bf16x8& pa1, bf16x8& pa2, bf16x8& pa3) {
; #pragma unroll
;   for (int r = 0; r < 16; ++r) p1[r] = __builtin_amdgcn_exp2f(p1[r]);
;   float ps = 0;
; #pragma unroll
;   for (int r = 0; r < 16; ++r) ps += p0[r];
; #pragma unroll
;   for (int r = 0; r < 16; ++r) ps += p1[r];
;   { auto rr = __builtin_amdgcn_permlane32_swap(__float_as_uint(ps), __float_as_uint(ps), false, false);
;     ps = __uint_as_float(rr[0]) + __uint_as_float(rr[1]); }
;   l_reg = l_reg * alpha + ps;
;     ...
;   PK4(p0, 0, pa0); PK4(p0, 8, pa1); PK4(p1, 0, pa2); PK4(p1, 8, pa3);
; template <int DQK, int KW, int QSP> __device__ __forceinline__ void qkt(f32x16& p0, f32x16& p1, const char* Ks, const int (&kb)[4], const bf16x8* qr, const char* qsp, const f32x16& cinit) {
;   p0 = cinit; p1 = cinit;
;   constexpr int N = DQK / 16;
;     ...
;   bf16x8 f0[2], f1[2];
;   f0[0] = KRD(0, 1); f1[0] = KRD(0, 0);
; #pragma unroll
;   for (int d0 = 0; d0 < N; ++d0) {
;     if (d0 + 1 < N) { f0[(d0 + 1) & 1] = KRD(d0 + 1, 1); f1[(d0 + 1) & 1] = KRD(d0 + 1, 0); }
;     __builtin_amdgcn_sched_barrier(0x406);
;     bf16x8 qf;
;     if constexpr (QSP > 0) { if (d0 >= N - QSP) qf = *reinterpret_cast<const bf16x8*>(qsp + (d0 - (N - QSP)) * 1024); else qf = qr[d0]; } else qf = qr[d0];
;     p0 = __builtin_amdgcn_mfma_f32_32x32x16_bf16(f0[d0 & 1], qf, p0, 0, 0, 0);
;     p1 = __builtin_amdgcn_mfma_f32_32x32x16_bf16(f1[d0 & 1], qf, p1, 0, 0, 0);
;     __builtin_amdgcn_sched_barrier(0x406); }
	s_add_u32 s6, s22, s6
	v_pk_fma_f32 v[130:131], v[32:33], s[90:91], v[68:69] op_sel_hi:[1,0,0]
	v_pk_fma_f32 v[132:133], v[30:31], s[90:91], v[68:69] op_sel_hi:[1,0,0]
	v_pk_fma_f32 v[134:135], v[28:29], s[90:91], v[68:69] op_sel_hi:[1,0,0]
	v_pk_fma_f32 v[136:137], v[26:27], s[90:91], v[68:69] op_sel_hi:[1,0,0]
	v_pk_fma_f32 v[138:139], v[24:25], s[90:91], v[68:69] op_sel_hi:[1,0,0]
	v_pk_fma_f32 v[140:141], v[22:23], s[90:91], v[68:69] op_sel_hi:[1,0,0]
	v_pk_fma_f32 v[142:143], v[20:21], s[90:91], v[68:69] op_sel_hi:[1,0,0]
	s_addc_u32 s7, s23, s8
	v_mov_b64_e32 v[64:65], v[16:17]
	v_mov_b64_e32 v[48:49], v[16:17]
	v_mov_b64_e32 v[32:33], v[16:17]
	v_lshl_add_u64 v[148:149], s[6:7], 0, v[66:67]
	v_mov_b64_e32 v[62:63], v[14:15]
	v_mov_b64_e32 v[60:61], v[12:13]
	v_mov_b64_e32 v[58:59], v[10:11]
	v_mov_b64_e32 v[56:57], v[8:9]
	v_mov_b64_e32 v[54:55], v[6:7]
	v_mov_b64_e32 v[52:53], v[4:5]
	v_mov_b64_e32 v[50:51], v[2:3]
	v_mov_b64_e32 v[46:47], v[14:15]
	v_mov_b64_e32 v[44:45], v[12:13]
	v_mov_b64_e32 v[42:43], v[10:11]
	v_mov_b64_e32 v[40:41], v[8:9]
	v_mov_b64_e32 v[38:39], v[6:7]
	v_mov_b64_e32 v[36:37], v[4:5]
	v_mov_b64_e32 v[34:35], v[2:3]
	v_mov_b64_e32 v[30:31], v[14:15]
	v_mov_b64_e32 v[28:29], v[12:13]
	v_mov_b64_e32 v[26:27], v[10:11]
	v_mov_b64_e32 v[24:25], v[8:9]
	v_mov_b64_e32 v[22:23], v[6:7]
	v_mov_b64_e32 v[20:21], v[4:5]
	v_mov_b64_e32 v[18:19], v[2:3]
.LBB0_286:
	s_lshl_b32 s8, s30, 14
	s_add_i32 s6, s8, 0
	v_add_u32_e32 v208, s6, v163
	v_add_u32_e32 v209, s6, v158
	ds_read_b128 v[168:171], v208 offset:49152
	ds_read_b128 v[196:199], v208 offset:57344
	ds_read_b128 v[66:69], v209 offset:57344
	ds_read_b128 v[70:73], v209 offset:49152
	v_add_u32_e32 v212, s6, v164
	v_add_u32_e32 v213, s6, v165
	s_waitcnt lgkmcnt(0)
	v_mfma_f32_32x32x16_bf16 v[82:97], v[70:73], v[102:105], 0
	v_exp_f32_e32 v144, v144
	v_exp_f32_e32 v145, v145
	v_exp_f32_e32 v142, v142
	v_exp_f32_e32 v143, v143
	v_exp_f32_e32 v140, v140
	v_exp_f32_e32 v141, v141
	v_mfma_f32_32x32x16_bf16 v[66:81], v[66:69], v[102:105], 0
	ds_read_b128 v[200:203], v212 offset:49152
	ds_read_b128 v[204:207], v212 offset:57344
	v_mfma_f32_32x32x16_bf16 v[82:97], v[168:171], v[110:113], v[82:97]
	v_mfma_f32_32x32x16_bf16 v[66:81], v[196:199], v[110:113], v[66:81]
	ds_read_b128 v[168:171], v213 offset:49152
	ds_read_b128 v[196:199], v213 offset:57344
	s_waitcnt lgkmcnt(3)
	v_mfma_f32_32x32x16_bf16 v[82:97], v[200:203], v[106:109], v[82:97]
	s_waitcnt lgkmcnt(2)
	v_mfma_f32_32x32x16_bf16 v[66:81], v[204:207], v[106:109], v[66:81]
	ds_read_b128 v[200:203], v209 offset:49280
	ds_read_b128 v[204:207], v209 offset:57472
	s_waitcnt lgkmcnt(3)
	v_mfma_f32_32x32x16_bf16 v[82:97], v[168:171], v[98:101], v[82:97]
	s_waitcnt lgkmcnt(2)
	v_mfma_f32_32x32x16_bf16 v[66:81], v[196:199], v[98:101], v[66:81]
	ds_read_b128 v[168:171], v208 offset:49280
	ds_read_b128 v[196:199], v208 offset:57472
	s_waitcnt lgkmcnt(3)
	v_mfma_f32_32x32x16_bf16 v[82:97], v[200:203], v[220:223], v[82:97]
	s_waitcnt lgkmcnt(2)
	v_mfma_f32_32x32x16_bf16 v[66:81], v[204:207], v[220:223], v[66:81]
	ds_read_b128 v[200:203], v212 offset:49280
	ds_read_b128 v[204:207], v212 offset:57472
	s_waitcnt lgkmcnt(3)
	v_mfma_f32_32x32x16_bf16 v[82:97], v[168:171], v[224:227], v[82:97]
	s_waitcnt lgkmcnt(2)
	v_mfma_f32_32x32x16_bf16 v[66:81], v[196:199], v[224:227], v[66:81]
	ds_read_b128 v[168:171], v213 offset:49280
	ds_read_b128 v[196:199], v213 offset:57472
	s_waitcnt lgkmcnt(3)
	v_mfma_f32_32x32x16_bf16 v[82:97], v[200:203], v[228:231], v[82:97]
	s_waitcnt lgkmcnt(2)
	v_mfma_f32_32x32x16_bf16 v[66:81], v[204:207], v[228:231], v[66:81]
	s_waitcnt lgkmcnt(0)
	v_mfma_f32_32x32x16_bf16 v[82:97], v[168:171], v[232:235], v[82:97]
	v_exp_f32_e32 v170, v138
	v_exp_f32_e32 v171, v139
	v_mfma_f32_32x32x16_bf16 v[66:81], v[196:199], v[232:235], v[66:81]
	v_exp_f32_e32 v202, v130
	v_add_f32_e32 v130, 0, v193
	v_add_f32_e32 v130, v195, v130
	v_add_f32_e32 v130, v183, v130
	v_add_f32_e32 v130, v194, v130
	v_add_f32_e32 v130, v181, v130
	v_add_f32_e32 v130, v192, v130
	v_add_f32_e32 v130, v180, v130
	v_add_f32_e32 v130, v182, v130
	v_add_f32_e32 v130, v177, v130
	v_add_f32_e32 v130, v179, v130
	v_add_f32_e32 v130, v175, v130
	v_add_f32_e32 v130, v178, v130
	v_add_f32_e32 v130, v173, v130
	v_add_f32_e32 v130, v176, v130
	v_add_f32_e32 v130, v172, v130
	v_add_f32_e32 v130, v174, v130
	v_add_f32_e32 v130, v144, v130
	v_add_f32_e32 v130, v145, v130
	v_add_f32_e32 v130, v142, v130
	v_add_f32_e32 v130, v143, v130
	v_exp_f32_e32 v196, v136
	v_add_f32_e32 v130, v140, v130
	v_exp_f32_e32 v197, v137
	v_add_f32_e32 v130, v141, v130
	v_exp_f32_e32 v198, v134
	v_add_f32_e32 v130, v170, v130
	v_exp_f32_e32 v199, v135
	v_add_f32_e32 v130, v171, v130
	v_exp_f32_e32 v200, v132
	v_add_f32_e32 v130, v196, v130
	v_exp_f32_e32 v201, v133
	v_add_f32_e32 v130, v197, v130
	v_add_f32_e32 v130, v198, v130
	v_exp_f32_e32 v203, v131
	v_add_f32_e32 v130, v199, v130
	v_add_f32_e32 v130, v200, v130
	v_add_f32_e32 v130, v201, v130
	v_add_f32_e32 v130, v202, v130
	v_add_f32_e32 v168, v203, v130
	v_mov_b32_e32 v169, v168
	v_cvt_pk_bf16_f32 v130, v193, v195
	v_cvt_pk_bf16_f32 v131, v183, v194
	v_cvt_pk_bf16_f32 v132, v181, v192
	s_nop 1
	v_permlane32_swap_b32_e32 v168, v169
	v_cvt_pk_bf16_f32 v133, v180, v182
	v_permlane32_swap_b32_e32 v130, v132
	v_cvt_pk_bf16_f32 v134, v177, v179
	v_cvt_pk_bf16_f32 v135, v175, v178
	v_cvt_pk_bf16_f32 v136, v173, v176
	v_cvt_pk_bf16_f32 v137, v172, v174
	v_cvt_pk_bf16_f32 v138, v144, v145
	v_cvt_pk_bf16_f32 v139, v142, v143
	v_cvt_pk_bf16_f32 v140, v140, v141
	v_cvt_pk_bf16_f32 v141, v170, v171
	v_cvt_pk_bf16_f32 v142, v196, v197
	v_cvt_pk_bf16_f32 v143, v198, v199
	v_cvt_pk_bf16_f32 v144, v200, v201
	v_cvt_pk_bf16_f32 v145, v202, v203
	v_permlane32_swap_b32_e32 v131, v133
	v_permlane32_swap_b32_e32 v134, v136
	v_permlane32_swap_b32_e32 v135, v137
	v_permlane32_swap_b32_e32 v138, v140
	v_permlane32_swap_b32_e32 v139, v141
	v_permlane32_swap_b32_e32 v142, v144
	v_permlane32_swap_b32_e32 v143, v145
	s_lshl_b32 s28, s27, 14
	s_add_i32 s9, s28, 0
	v_add_u32_e32 v170, s9, v159
	s_waitcnt vmcnt(0)
; #define SBAR() __builtin_amdgcn_sched_barrier(0)
; template <int D0> __device__ __forceinline__ void pv_one(f32x16& od, int vb, bf16x8 pa0, bf16x8 pa1, bf16x8 pa2, bf16x8 pa3) {
;   const s16x4 l0 = tr_read<v_rd_off(D0, 0, 0)>(vb), h0 = tr_read<v_rd_off(D0, 0, 1)>(vb), l1 = tr_read<v_rd_off(D0, 1, 0)>(vb), h1 = tr_read<v_rd_off(D0, 1, 1)>(vb);
;   const s16x4 l2 = tr_read<v_rd_off(D0, 2, 0)>(vb), h2 = tr_read<v_rd_off(D0, 2, 1)>(vb), l3 = tr_read<v_rd_off(D0, 3, 0)>(vb), h3 = tr_read<v_rd_off(D0, 3, 1)>(vb);
;   asm volatile("s_waitcnt lgkmcnt(0)" ::: "memory"); SBAR();
;     ...
;   od = __builtin_amdgcn_mfma_f32_32x32x16_bf16(pa0, PK(l0, h0), od, 0, 0, 0);
;   od = __builtin_amdgcn_mfma_f32_32x32x16_bf16(pa1, PK(l1, h1), od, 0, 0, 0);
;   od = __builtin_amdgcn_mfma_f32_32x32x16_bf16(pa2, PK(l2, h2), od, 0, 0, 0);
;   od = __builtin_amdgcn_mfma_f32_32x32x16_bf16(pa3, PK(l3, h3), od, 0, 0, 0);
;     ...
; }
; __device__ __forceinline__ void pv_d0(f32x16* o, int vb, bf16x8 pa0, bf16x8 pa1, bf16x8 pa2, bf16x8 pa3) {
;   pv_one<0>(o[0], vb, pa0, pa1, pa2, pa3); pv_one<1>(o[1], vb, pa0, pa1, pa2, pa3); pv_one<2>(o[2], vb, pa0, pa1, pa2, pa3); pv_one<3>(o[3], vb, pa0, pa1, pa2, pa3);
; }
	s_waitcnt vmcnt(3)
	ds_write_b128 v170, v[114:117]
	v_add_u32_e32 v114, s9, v160
	s_waitcnt vmcnt(1)
	ds_write_b128 v114, v[118:121]
	v_add_u32_e32 v114, s9, v161
	s_mov_b32 s6, 0xfffe8000
	s_waitcnt vmcnt(1)
	ds_write_b128 v114, v[122:125] offset:49152
	s_waitcnt vmcnt(0)
	ds_write_b128 v114, v[126:129] offset:57344
	v_add_co_u32_e32 v114, vcc, s6, v148
	s_mov_b32 s6, 0xfb7e8000
	s_nop 0
	v_addc_co_u32_e32 v115, vcc, -1, v149, vcc
	v_add_co_u32_e32 v118, vcc, s3, v148
	s_nop 1
	v_addc_co_u32_e32 v119, vcc, -1, v149, vcc
	v_add_co_u32_e32 v122, vcc, s6, v148
	s_mov_b32 s6, 0xfb7f0000
	s_nop 0
	v_addc_co_u32_e32 v123, vcc, -1, v149, vcc
	v_add_co_u32_e32 v126, vcc, s6, v148
	global_load_dwordx4 v[114:117], v[114:115], off
	s_nop 0
	global_load_dwordx4 v[118:121], v[118:119], off
	v_addc_co_u32_e32 v127, vcc, -1, v149, vcc
	global_load_dwordx4 v[122:125], v[122:123], off
	s_nop 0
	global_load_dwordx4 v[126:129], v[126:127], off
	v_lshl_add_u32 v182, s48, 14, v154
	ds_read_b64_tr_b16 v[170:171], v182 offset:0
	ds_read_b64_tr_b16 v[172:173], v182 offset:0x800
	ds_read_b64_tr_b16 v[174:175], v182 offset:0x1000
	ds_read_b64_tr_b16 v[176:177], v182 offset:0x1800
	ds_read_b64_tr_b16 v[178:179], v182 offset:0x2000
	ds_read_b64_tr_b16 v[180:181], v182 offset:0x2800
	ds_read_b64_tr_b16 v[192:193], v182 offset:0x3000
	ds_read_b64_tr_b16 v[194:195], v182 offset:0x3800
	s_waitcnt lgkmcnt(0)
	s_nop 0
	v_mfma_f32_32x32x16_bf16 v[2:17], v[130:133], v[170:173], v[2:17]
	ds_read_b64_tr_b16 v[170:171], v182 offset:0x200
	ds_read_b64_tr_b16 v[172:173], v182 offset:0xa00
	v_mfma_f32_32x32x16_bf16 v[2:17], v[134:137], v[174:177], v[2:17]
	ds_read_b64_tr_b16 v[174:175], v182 offset:0x1200
	ds_read_b64_tr_b16 v[176:177], v182 offset:0x1a00
	v_mfma_f32_32x32x16_bf16 v[2:17], v[138:141], v[178:181], v[2:17]
	ds_read_b64_tr_b16 v[178:179], v182 offset:0x2200
	ds_read_b64_tr_b16 v[180:181], v182 offset:0x2a00
	v_mfma_f32_32x32x16_bf16 v[2:17], v[142:145], v[192:195], v[2:17]
	ds_read_b64_tr_b16 v[192:193], v182 offset:0x3200
	ds_read_b64_tr_b16 v[194:195], v182 offset:0x3a00
	s_waitcnt lgkmcnt(0)
	v_mfma_f32_32x32x16_bf16 v[50:65], v[130:133], v[170:173], v[50:65]
	ds_read_b64_tr_b16 v[170:171], v182 offset:0x400
	ds_read_b64_tr_b16 v[172:173], v182 offset:0xc00
	v_mfma_f32_32x32x16_bf16 v[50:65], v[134:137], v[174:177], v[50:65]
	ds_read_b64_tr_b16 v[174:175], v182 offset:0x1400
	ds_read_b64_tr_b16 v[176:177], v182 offset:0x1c00
	v_mfma_f32_32x32x16_bf16 v[50:65], v[138:141], v[178:181], v[50:65]
	ds_read_b64_tr_b16 v[178:179], v182 offset:0x2400
	ds_read_b64_tr_b16 v[180:181], v182 offset:0x2c00
	v_mfma_f32_32x32x16_bf16 v[50:65], v[142:145], v[192:195], v[50:65]
	ds_read_b64_tr_b16 v[192:193], v182 offset:0x3400
	ds_read_b64_tr_b16 v[194:195], v182 offset:0x3c00
	s_waitcnt lgkmcnt(0)
	v_mfma_f32_32x32x16_bf16 v[34:49], v[130:133], v[170:173], v[34:49]
	ds_read_b64_tr_b16 v[170:171], v182 offset:0x600
	ds_read_b64_tr_b16 v[172:173], v182 offset:0xe00
	v_mfma_f32_32x32x16_bf16 v[34:49], v[134:137], v[174:177], v[34:49]
	ds_read_b64_tr_b16 v[174:175], v182 offset:0x1600
	ds_read_b64_tr_b16 v[176:177], v182 offset:0x1e00
	v_mfma_f32_32x32x16_bf16 v[34:49], v[138:141], v[178:181], v[34:49]
	ds_read_b64_tr_b16 v[178:179], v182 offset:0x2600
	ds_read_b64_tr_b16 v[180:181], v182 offset:0x2e00
	v_mfma_f32_32x32x16_bf16 v[34:49], v[142:145], v[192:195], v[34:49]
	ds_read_b64_tr_b16 v[192:193], v182 offset:0x3600
	ds_read_b64_tr_b16 v[194:195], v182 offset:0x3e00
	s_waitcnt lgkmcnt(0)
	v_mfma_f32_32x32x16_bf16 v[18:33], v[130:133], v[170:173], v[18:33]
	v_max_f32_e32 v130, v83, v83
	v_max_f32_e32 v131, v82, v82
	v_max_f32_e32 v130, v131, v130
	v_max3_f32 v130, v130, v84, v85
	v_max3_f32 v130, v130, v86, v87
	v_max3_f32 v130, v130, v88, v89
	v_max3_f32 v130, v130, v90, v91
	v_max3_f32 v130, v130, v92, v93
	v_max3_f32 v130, v130, v94, v95
	v_mfma_f32_32x32x16_bf16 v[18:33], v[134:137], v[174:177], v[18:33]
	v_max3_f32 v130, v130, v96, v97
	v_max3_f32 v130, v130, v66, v67
	v_max3_f32 v130, v130, v68, v69
	v_max3_f32 v130, v130, v70, v71
	v_max3_f32 v130, v130, v72, v73
	v_max3_f32 v130, v130, v74, v75
	v_max3_f32 v130, v130, v76, v77
	v_max3_f32 v130, v130, v78, v79
	v_mfma_f32_32x32x16_bf16 v[18:33], v[138:141], v[178:181], v[18:33]
	v_max3_f32 v130, v130, v80, v81
	v_mov_b32_e32 v131, v130
	s_nop 1
	v_permlane32_swap_b32_e32 v130, v131
	v_max_f32_e32 v131, v131, v131
	v_max_f32_e32 v130, v130, v130
	v_max_f32_e32 v130, v130, v131
	v_sub_f32_e32 v131, v130, v167
	v_cmp_ge_f32_e32 vcc, s33, v131
	v_max_f32_e32 v131, v167, v167
	v_max_f32_e32 v130, v131, v130
	v_mfma_f32_32x32x16_bf16 v[18:33], v[142:145], v[192:195], v[18:33]
	v_sub_f32_e32 v131, v167, v130
	v_mul_f32_e32 v131, 0x3e0293ee, v131
	v_exp_f32_e32 v131, v131
	s_cmp_eq_u64 vcc, exec
	s_cselect_b64 s[40:41], -1, 0
	s_waitcnt lgkmcnt(0)
	s_barrier
	v_cndmask_b32_e64 v171, v131, 1.0, s[40:41]
	v_cmp_gt_f32_e32 vcc, 1.0, v171
	s_cbranch_vccz .LBB0_290
	s_and_saveexec_b64 s[6:7], s[38:39]
	ds_write_b32 v155, v171 offset:128
	s_or_b64 exec, exec, s[6:7]
	s_waitcnt lgkmcnt(0)
	v_add_u32_e32 v131, v153, v146
	ds_read_b128 v[132:135], v131 offset:224
	ds_read_b128 v[136:139], v131 offset:192
	ds_read_b128 v[140:143], v131 offset:160
	ds_read_b128 v[172:175], v131 offset:128
	s_waitcnt lgkmcnt(3)
	v_pk_mul_f32 v[14:15], v[14:15], v[132:133]
	s_waitcnt lgkmcnt(2)
	v_pk_mul_f32 v[10:11], v[10:11], v[136:137]
	s_waitcnt lgkmcnt(1)
	v_pk_mul_f32 v[6:7], v[6:7], v[140:141]
	v_pk_mul_f32 v[16:17], v[16:17], v[134:135]
	v_pk_mul_f32 v[12:13], v[12:13], v[138:139]
	v_pk_mul_f32 v[8:9], v[8:9], v[142:143]
	s_waitcnt lgkmcnt(0)
	v_pk_mul_f32 v[4:5], v[4:5], v[174:175]
	v_pk_mul_f32 v[2:3], v[2:3], v[172:173]
	v_pk_mul_f32 v[62:63], v[62:63], v[132:133]
	v_pk_mul_f32 v[58:59], v[58:59], v[136:137]
	v_pk_mul_f32 v[54:55], v[54:55], v[140:141]
	v_pk_mul_f32 v[64:65], v[64:65], v[134:135]
	v_pk_mul_f32 v[60:61], v[60:61], v[138:139]
	v_pk_mul_f32 v[56:57], v[56:57], v[142:143]
	v_pk_mul_f32 v[52:53], v[52:53], v[174:175]
	v_pk_mul_f32 v[50:51], v[50:51], v[172:173]
	v_pk_mul_f32 v[46:47], v[46:47], v[132:133]
	v_pk_mul_f32 v[42:43], v[42:43], v[136:137]
	v_pk_mul_f32 v[38:39], v[38:39], v[140:141]
	v_pk_mul_f32 v[48:49], v[48:49], v[134:135]
	v_pk_mul_f32 v[44:45], v[44:45], v[138:139]
	v_pk_mul_f32 v[40:41], v[40:41], v[142:143]
	v_pk_mul_f32 v[36:37], v[36:37], v[174:175]
	v_pk_mul_f32 v[34:35], v[34:35], v[172:173]
	v_pk_mul_f32 v[30:31], v[30:31], v[132:133]
	v_pk_mul_f32 v[26:27], v[26:27], v[136:137]
	v_pk_mul_f32 v[22:23], v[22:23], v[140:141]
	v_pk_mul_f32 v[32:33], v[32:33], v[134:135]
	v_pk_mul_f32 v[28:29], v[28:29], v[138:139]
	v_pk_mul_f32 v[24:25], v[24:25], v[142:143]
	v_pk_mul_f32 v[20:21], v[20:21], v[174:175]
	v_pk_mul_f32 v[18:19], v[18:19], v[172:173]
; template <int DQK> __device__ __forceinline__ void partialSM(f32x16& p0, f32x16& p1, float& m_reg, float& mn, float& alpha) {
;     ...
;   else { mn = fmaxf(m_reg, pmax); alpha = __builtin_amdgcn_exp2f((m_reg - mn) * C); m_reg = mn; }
;   float mnC = -mn * C;
; #pragma unroll
;   for (int r = 0; r < 16; ++r) p0[r] = fmaf(p0[r], C, mnC);
; #pragma unroll
;   for (int r = 0; r < 16; ++r) p1[r] = fmaf(p1[r], C, mnC);
; #pragma unroll
;   for (int r = 0; r < 16; ++r) p0[r] = __builtin_amdgcn_exp2f(p0[r]);
; __device__ __forceinline__ void finishSM(f32x16& p0, f32x16& p1, float alpha, float& l_reg, bf16x8& pa0, bf16x8& pa1, bf16x8& pa2, bf16x8& pa3) {
; #pragma unroll
;   for (int r = 0; r < 16; ++r) p1[r] = __builtin_amdgcn_exp2f(p1[r]);
;   float ps = 0;
; #pragma unroll
;   for (int r = 0; r < 16; ++r) ps += p0[r];
; #pragma unroll
;   for (int r = 0; r < 16; ++r) ps += p1[r];
;   { auto rr = __builtin_amdgcn_permlane32_swap(__float_as_uint(ps), __float_as_uint(ps), false, false);
;     ps = __uint_as_float(rr[0]) + __uint_as_float(rr[1]); }
;   l_reg = l_reg * alpha + ps;
;     ...
;   PK4(p0, 0, pa0); PK4(p0, 8, pa1); PK4(p1, 0, pa2); PK4(p1, 8, pa3);
; template <int DQK, int KW, int QSP> __device__ __forceinline__ void qkt(f32x16& p0, f32x16& p1, const char* Ks, const int (&kb)[4], const bf16x8* qr, const char* qsp, const f32x16& cinit) {
;   p0 = cinit; p1 = cinit;
;   constexpr int N = DQK / 16;
;     ...
;   bf16x8 f0[2], f1[2];
;   f0[0] = KRD(0, 1); f1[0] = KRD(0, 0);
; #pragma unroll
;   for (int d0 = 0; d0 < N; ++d0) {
;     if (d0 + 1 < N) { f0[(d0 + 1) & 1] = KRD(d0 + 1, 1); f1[(d0 + 1) & 1] = KRD(d0 + 1, 0); }
;     __builtin_amdgcn_sched_barrier(0x406);
;     bf16x8 qf;
;     if constexpr (QSP > 0) { if (d0 >= N - QSP) qf = *reinterpret_cast<const bf16x8*>(qsp + (d0 - (N - QSP)) * 1024); else qf = qr[d0]; } else qf = qr[d0];
;     p0 = __builtin_amdgcn_mfma_f32_32x32x16_bf16(f0[d0 & 1], qf, p0, 0, 0, 0);
;     p1 = __builtin_amdgcn_mfma_f32_32x32x16_bf16(f1[d0 & 1], qf, p1, 0, 0, 0);
;     __builtin_amdgcn_sched_barrier(0x406); }
.LBB0_290:
	v_cndmask_b32_e64 v167, v130, v167, s[40:41]
	s_add_i32 s6, s27, 1
	v_mul_f32_e32 v170, 0xbe0293ee, v167
	s_cmp_lg_u32 s27, 2
	v_fmamk_f32 v82, v82, 0x3e0293ee, v170
	v_fmamk_f32 v83, v83, 0x3e0293ee, v170
	v_fmamk_f32 v84, v84, 0x3e0293ee, v170
	v_fmamk_f32 v85, v85, 0x3e0293ee, v170
	v_fmamk_f32 v86, v86, 0x3e0293ee, v170
	v_fmamk_f32 v87, v87, 0x3e0293ee, v170
	v_fmamk_f32 v88, v88, 0x3e0293ee, v170
	v_fmamk_f32 v89, v89, 0x3e0293ee, v170
	v_fmamk_f32 v90, v90, 0x3e0293ee, v170
	v_fmamk_f32 v91, v91, 0x3e0293ee, v170
	v_fmamk_f32 v92, v92, 0x3e0293ee, v170
	v_fmamk_f32 v93, v93, 0x3e0293ee, v170
	v_fmamk_f32 v94, v94, 0x3e0293ee, v170
	v_fmamk_f32 v95, v95, 0x3e0293ee, v170
	v_fmamk_f32 v96, v96, 0x3e0293ee, v170
	v_fmamk_f32 v97, v97, 0x3e0293ee, v170
	v_fmamk_f32 v196, v78, 0x3e0293ee, v170
	v_fmamk_f32 v197, v79, 0x3e0293ee, v170
	s_cselect_b32 s30, s6, 0
	v_fmamk_f32 v176, v66, 0x3e0293ee, v170
	v_fmamk_f32 v177, v67, 0x3e0293ee, v170
	v_fmamk_f32 v178, v68, 0x3e0293ee, v170
	v_fmamk_f32 v179, v69, 0x3e0293ee, v170
	v_fmamk_f32 v180, v70, 0x3e0293ee, v170
	v_fmamk_f32 v181, v71, 0x3e0293ee, v170
	v_fmamk_f32 v182, v72, 0x3e0293ee, v170
	v_fmamk_f32 v183, v73, 0x3e0293ee, v170
	v_fmamk_f32 v192, v74, 0x3e0293ee, v170
	v_fmamk_f32 v193, v75, 0x3e0293ee, v170
	v_fmamk_f32 v194, v76, 0x3e0293ee, v170
	v_fmamk_f32 v195, v77, 0x3e0293ee, v170
	v_fmamk_f32 v198, v80, 0x3e0293ee, v170
	v_fmac_f32_e32 v170, 0x3e0293ee, v81
	v_exp_f32_e32 v199, v82
	v_exp_f32_e32 v200, v83
	v_exp_f32_e32 v201, v84
	v_exp_f32_e32 v202, v85
	v_exp_f32_e32 v203, v86
	v_exp_f32_e32 v204, v87
	v_exp_f32_e32 v205, v88
	v_exp_f32_e32 v206, v89
	v_exp_f32_e32 v207, v90
	v_exp_f32_e32 v208, v91
	v_exp_f32_e32 v209, v92
	v_exp_f32_e32 v210, v93
	v_exp_f32_e32 v211, v94
	v_exp_f32_e32 v212, v95
	v_exp_f32_e32 v213, v96
	v_exp_f32_e32 v214, v97
	v_add_u32_e32 v172, s9, v163
	v_add_u32_e32 v173, s9, v158
	ds_read_b128 v[130:133], v172 offset:49152
	ds_read_b128 v[134:137], v172 offset:57344
	ds_read_b128 v[66:69], v173 offset:57344
	ds_read_b128 v[70:73], v173 offset:49152
	v_add_u32_e32 v215, s9, v164
	v_add_u32_e32 v216, s9, v165
	s_waitcnt lgkmcnt(0)
	v_mfma_f32_32x32x16_bf16 v[82:97], v[70:73], v[102:105], 0
	v_exp_f32_e32 v170, v170
	v_mfma_f32_32x32x16_bf16 v[66:81], v[66:69], v[102:105], 0
	ds_read_b128 v[138:141], v215 offset:49152
	ds_read_b128 v[142:145], v215 offset:57344
	v_mfma_f32_32x32x16_bf16 v[82:97], v[130:133], v[110:113], v[82:97]
	v_mfma_f32_32x32x16_bf16 v[66:81], v[134:137], v[110:113], v[66:81]
	ds_read_b128 v[130:133], v216 offset:49152
	ds_read_b128 v[134:137], v216 offset:57344
	s_waitcnt lgkmcnt(3)
	v_mfma_f32_32x32x16_bf16 v[82:97], v[138:141], v[106:109], v[82:97]
	s_waitcnt lgkmcnt(2)
	v_mfma_f32_32x32x16_bf16 v[66:81], v[142:145], v[106:109], v[66:81]
	ds_read_b128 v[138:141], v173 offset:49280
	ds_read_b128 v[142:145], v173 offset:57472
	s_waitcnt lgkmcnt(3)
	v_mfma_f32_32x32x16_bf16 v[82:97], v[130:133], v[98:101], v[82:97]
	s_waitcnt lgkmcnt(2)
	v_mfma_f32_32x32x16_bf16 v[66:81], v[134:137], v[98:101], v[66:81]
	ds_read_b128 v[130:133], v172 offset:49280
	ds_read_b128 v[134:137], v172 offset:57472
	s_waitcnt lgkmcnt(3)
	v_mfma_f32_32x32x16_bf16 v[82:97], v[138:141], v[220:223], v[82:97]
	s_waitcnt lgkmcnt(2)
	v_mfma_f32_32x32x16_bf16 v[66:81], v[142:145], v[220:223], v[66:81]
	ds_read_b128 v[138:141], v215 offset:49280
	ds_read_b128 v[142:145], v215 offset:57472
	s_waitcnt lgkmcnt(3)
	v_mfma_f32_32x32x16_bf16 v[82:97], v[130:133], v[224:227], v[82:97]
	s_waitcnt lgkmcnt(2)
	v_mfma_f32_32x32x16_bf16 v[66:81], v[134:137], v[224:227], v[66:81]
	ds_read_b128 v[130:133], v216 offset:49280
	ds_read_b128 v[134:137], v216 offset:57472
	s_waitcnt lgkmcnt(3)
	v_mfma_f32_32x32x16_bf16 v[82:97], v[138:141], v[228:231], v[82:97]
	s_waitcnt lgkmcnt(2)
	v_mfma_f32_32x32x16_bf16 v[66:81], v[142:145], v[228:231], v[66:81]
	v_exp_f32_e32 v142, v180
	v_exp_f32_e32 v143, v181
	v_exp_f32_e32 v144, v182
	v_exp_f32_e32 v145, v183
	v_exp_f32_e32 v172, v192
	v_exp_f32_e32 v173, v193
	s_waitcnt lgkmcnt(0)
	v_mfma_f32_32x32x16_bf16 v[82:97], v[130:133], v[232:235], v[82:97]
	v_add_f32_e32 v130, 0, v199
	v_add_f32_e32 v130, v200, v130
	v_add_f32_e32 v130, v201, v130
	v_add_f32_e32 v130, v202, v130
	v_add_f32_e32 v130, v203, v130
	v_add_f32_e32 v130, v204, v130
	v_add_f32_e32 v130, v205, v130
	v_add_f32_e32 v130, v206, v130
	v_add_f32_e32 v130, v207, v130
	v_add_f32_e32 v130, v208, v130
	v_add_f32_e32 v130, v209, v130
	v_add_f32_e32 v130, v210, v130
	v_mfma_f32_32x32x16_bf16 v[66:81], v[134:137], v[232:235], v[66:81]
	v_exp_f32_e32 v138, v176
	v_add_f32_e32 v130, v211, v130
	v_exp_f32_e32 v139, v177
	v_add_f32_e32 v130, v212, v130
	v_exp_f32_e32 v140, v178
	v_add_f32_e32 v130, v213, v130
	v_exp_f32_e32 v141, v179
	v_add_f32_e32 v130, v214, v130
	v_add_f32_e32 v130, v138, v130
	v_add_f32_e32 v130, v139, v130
	v_add_f32_e32 v130, v140, v130
	v_add_f32_e32 v130, v141, v130
	v_add_f32_e32 v130, v142, v130
	v_add_f32_e32 v130, v143, v130
	v_exp_f32_e32 v174, v194
	v_add_f32_e32 v130, v144, v130
	v_exp_f32_e32 v175, v195
	v_add_f32_e32 v130, v145, v130
	v_exp_f32_e32 v176, v196
	v_add_f32_e32 v130, v172, v130
	v_exp_f32_e32 v177, v197
	v_add_f32_e32 v130, v173, v130
	v_exp_f32_e32 v178, v198
	v_add_f32_e32 v130, v174, v130
	v_add_f32_e32 v130, v175, v130
	v_add_f32_e32 v130, v176, v130
	v_add_f32_e32 v130, v177, v130
	v_add_f32_e32 v130, v178, v130
	v_add_f32_e32 v196, v170, v130
	v_mov_b32_e32 v197, v196
	v_cvt_pk_bf16_f32 v130, v199, v200
	v_cvt_pk_bf16_f32 v131, v201, v202
	v_cvt_pk_bf16_f32 v132, v203, v204
	v_cvt_pk_bf16_f32 v133, v205, v206
	v_cvt_pk_bf16_f32 v134, v207, v208
	v_cvt_pk_bf16_f32 v135, v209, v210
	v_cvt_pk_bf16_f32 v136, v211, v212
	v_cvt_pk_bf16_f32 v137, v213, v214
	v_cvt_pk_bf16_f32 v138, v138, v139
	v_cvt_pk_bf16_f32 v139, v140, v141
	v_cvt_pk_bf16_f32 v140, v142, v143
	v_cvt_pk_bf16_f32 v141, v144, v145
	v_cvt_pk_bf16_f32 v142, v172, v173
	v_cvt_pk_bf16_f32 v143, v174, v175
	v_cvt_pk_bf16_f32 v144, v176, v177
	v_cvt_pk_bf16_f32 v145, v178, v170
	s_nop 1
	v_permlane32_swap_b32_e32 v196, v197
	v_permlane32_swap_b32_e32 v130, v132
	v_permlane32_swap_b32_e32 v131, v133
	v_permlane32_swap_b32_e32 v134, v136
	v_permlane32_swap_b32_e32 v135, v137
	v_permlane32_swap_b32_e32 v138, v140
	v_permlane32_swap_b32_e32 v139, v141
	v_permlane32_swap_b32_e32 v142, v144
	v_permlane32_swap_b32_e32 v143, v145
	s_lshl_b32 s29, s30, 14
	s_add_i32 s31, s29, 0
	s_waitcnt vmcnt(0)
	v_add_u32_e32 v170, s31, v159
	s_cmp_ge_u32 s25, s26
	s_waitcnt vmcnt(3)
	ds_write_b128 v170, v[114:117]
	v_add_u32_e32 v170, s31, v160
	s_cselect_b64 s[6:7], -1, 0
	s_waitcnt vmcnt(2)
	ds_write_b128 v170, v[118:121]
	v_add_u32_e32 v170, s29, v162
	s_and_b64 vcc, exec, s[6:7]
	s_waitcnt vmcnt(1)
	ds_write_b128 v170, v[122:125] offset:49152
	s_waitcnt vmcnt(0)
	ds_write_b128 v170, v[126:129] offset:57344
	s_cbranch_vccnz .LBB0_292
	v_add_co_u32_e32 v114, vcc, 0xffff8000, v148
	s_nop 1
	v_addc_co_u32_e32 v115, vcc, -1, v149, vcc
	v_add_co_u32_e32 v118, vcc, 0xfb7f8000, v148
	s_nop 1
	v_addc_co_u32_e32 v119, vcc, -1, v149, vcc
	v_add_co_u32_e32 v126, vcc, 0xfb800000, v148
	global_load_dwordx4 v[114:117], v[114:115], off
	s_nop 0
	global_load_dwordx4 v[122:125], v[118:119], off
	v_addc_co_u32_e32 v127, vcc, -1, v149, vcc
	global_load_dwordx4 v[118:121], v[148:149], off
	s_nop 0
	global_load_dwordx4 v[126:129], v[126:127], off
